# late conversion pass dealt to three positions (before P2 / between P2 and P3 / after P3) by (blockIdx>>3)%3
# baseline (speedup 1.0000x reference)
.Lp0_late_ret:
	s_lshr_b32 s100, s2, 3
	s_mul_i32 s101, s100, 0xab
	s_lshr_b32 s101, s101, 9
	s_mul_i32 s101, s101, 3
	s_sub_u32 s100, s100, s101
	s_cmp_eq_u32 s100, 2
	s_cbranch_scc1 .Lp3_ret
	s_cmp_eq_u32 s100, 1
	s_cbranch_scc1 .LBB0_284
	s_branch .Lp2_body

.LBB0_253:
	s_cmp_lt_i32 s8, 3
	s_cselect_b64 s[0:1], -1, 0
	s_cmp_gt_i32 s9, 2
	s_cselect_b64 s[4:5], -1, 0
	s_and_b64 s[0:1], s[0:1], s[4:5]
	s_andn2_b64 vcc, exec, s[0:1]
	s_cbranch_vccnz .LBB0_284
	s_lshr_b32 s100, s2, 3
	s_mul_i32 s101, s100, 0xab
	s_lshr_b32 s101, s101, 9
	s_mul_i32 s101, s101, 3
	s_sub_u32 s100, s100, s101
	s_cmp_lg_u32 s100, 0
	s_cbranch_scc1 .Lp2_body
	s_mov_b32 s99, 0
	s_branch .Lp0_body

.LBB0_283:
	s_waitcnt lgkmcnt(0)
	s_barrier
	s_lshr_b32 s100, s2, 3
	s_mul_i32 s101, s100, 0xab
	s_lshr_b32 s101, s101, 9
	s_mul_i32 s101, s101, 3
	s_sub_u32 s100, s100, s101
	s_cmp_eq_u32 s100, 1
	s_cbranch_scc0 .LBB0_284
	s_mov_b32 s99, 0
	s_waitcnt vmcnt(0)
	s_branch .Lp0_body

.LBB0_327:
	s_lshr_b32 s100, s2, 3
	s_mul_i32 s101, s100, 0xab
	s_lshr_b32 s101, s101, 9
	s_mul_i32 s101, s101, 3
	s_sub_u32 s100, s100, s101
	s_cmp_eq_u32 s100, 2
	s_cbranch_scc0 .Lp3_done
	s_mov_b32 s99, 0
	s_waitcnt vmcnt(0) lgkmcnt(0)
	s_barrier
	s_branch .Lp0_body
